# XCD-pair-scoped grid barriers (global only right after weight-conversion slots) with a run-time placement check that falls back to global barriers; attention units remapped pair-local; indexer/band an
# baseline (speedup 1.0000x reference)
; #define LAS __attribute__((address_space(3)))
; __device__ __forceinline__ unsigned xb_add(unsigned* p, unsigned v) { return __hip_atomic_fetch_add(p, v, __ATOMIC_RELAXED, __HIP_MEMORY_SCOPE_AGENT); }
; __device__ __forceinline__ unsigned xb_xcc_id() { return (unsigned)__builtin_amdgcn_s_getreg((3 << 11) | 20) & 0xFu; }
; __device__ __forceinline__ XcdBarrier xcd_barrier_post(unsigned* bar, volatile LAS unsigned* st) {
;     XcdBarrier b; b.bar = bar; b.x = xb_xcc_id(); b.st = st;
;     if (threadIdx.x == 0) (void)xb_add(&bar[XB_XCNT(b.x)], 1u);
;     return b;
; }
.LBB11_6:
	s_or_b64 exec, exec, s[2:3]
	v_readlane_b32 s12, v249, 17
	v_readlane_b32 s26, v249, 31
	s_waitcnt lgkmcnt(0)
	s_barrier
	v_readlane_b32 s27, v249, 32
	s_add_u32 s0, s26, 0x4000
	s_getreg_b32 s2, hwreg(HW_REG_XCC_ID, 0, 4)
	s_addc_u32 s1, s27, 0
	s_and_b32 s33, s2, 15
	v_readlane_b32 s13, v249, 18
	v_readlane_b32 s14, v249, 19
	v_readlane_b32 s15, v249, 20
	v_readlane_b32 s16, v249, 21
	v_readlane_b32 s17, v249, 22
	v_readlane_b32 s18, v249, 23
	v_readlane_b32 s19, v249, 24
	v_readlane_b32 s20, v249, 25
	v_readlane_b32 s21, v249, 26
	v_readlane_b32 s22, v249, 27
	v_readlane_b32 s23, v249, 28
	v_readlane_b32 s24, v249, 29
	v_readlane_b32 s25, v249, 30
	v_cmp_eq_u32_e64 s[4:5], 0, v0
	s_mov_b64 s[2:3], exec
	s_nop 0
	v_writelane_b32 v249, s4, 38
	s_nop 1
	v_writelane_b32 v249, s5, 39
	s_and_b64 s[4:5], s[2:3], s[4:5]
	s_mov_b64 exec, s[4:5]
	s_cbranch_execz .LBB11_9
	s_mov_b64 s[4:5], exec
	v_mbcnt_lo_u32_b32 v1, s4, 0
	v_mbcnt_hi_u32_b32 v1, s5, v1
	v_cmp_eq_u32_e32 vcc, 0, v1
	s_and_b64 s[6:7], exec, vcc
	s_mov_b64 exec, s[6:7]
	s_cbranch_execz .LBB11_9
	s_lshl_b32 s6, s33, 8
	s_bcnt1_i32_b64 s4, s[4:5]
	v_mov_b32_e32 v1, s6
	v_mov_b32_e32 v2, s4
	global_atomic_add v1, v2, s[0:1] offset:1024
	v_readlane_b32 s6, v249, 0
	s_and_b32 s6, s6, 7
	s_lshl_b32 s6, 1, s6
	v_mov_b32_e32 v2, s6
	s_lshl_b32 s6, s33, 2
	s_addk_i32 s6, 0x4000
	v_mov_b32_e32 v1, s6
	global_atomic_or v1, v2, s[0:1]

; #define LAS __attribute__((address_space(3)))
; #define STEP_BEGIN(idx, flag) if (lo <= (idx) && (idx) < hi) { for (int rep_ = 0; rep_ < (((REPEAT_MASK) & (flag)) ? 2 : 1); ++rep_) { if (prev) xcd_barrier(bar); prev = true; int lane = lane_k, wave = wave_k; size_t wz_ = 0; asm volatile("" : "+v"(lane), "+s"(wave), "+s"(wz_)); unsigned char* ws = ws_k + wz_;     const int gw = blockIdx.x * 8 + wave; (void)gw; (void)lane;
; __device__ __forceinline__ void xcd_barrier(const XcdBarrier& b) {
;     ...
;         unsigned* bar = b.bar;
;         __builtin_amdgcn_s_waitcnt(0);
;         unsigned nloc = b.st[0], nx = b.st[1];
;         if (nloc == 0u) { xcd_barrier_complete(bar, b.x, nloc, nx); b.st[0] = nloc; b.st[1] = nx; }
; __global__ void __launch_bounds__(512, 2) k_mega(MegaArgs a) {
;     ...
;             STEP_BEGIN(base + 0, F_FFN_IN) { pg8::EpiSwiglu E{H, FFN}; run_gemm(lds, XB, (const bf16_t*)(ws + WS_WF_FFN_IN + lj * SZ_FFN_IN), MT, 2 * FFN, DM, E);
;                 if (gridDim.x == 256 && blockIdx.x >= 128 && rep_ == 0) {
;                     int g_lo, g_hi; sched_tail(l, kind == 3 ? 1 : 0, g_lo, g_hi);
;                     convert_stream(a, g_lo, g_hi, (blockIdx.x - 128) * 8 + wave, 1024, (LAS float*)(lds + wave * 8448), lane); }
;             } STEP_END
.LBB11_446:
	s_or_b64 exec, exec, s[4:5]
	s_waitcnt lgkmcnt(0)
	s_barrier
	s_cmp_lg_u32 s100, 1
	s_cbranch_scc1 .Lsg_ffn
	v_readlane_b32 s101, v249, 0
	s_and_b32 s101, s101, 6
	s_lshl_b32 s101, s101, 8
	s_addk_i32 s101, 0x400
	v_readlane_b32 s100, v250, 49
	s_sub_u32 s100, s100, s101
	v_writelane_b32 v250, s100, 49
	s_nop 1
	v_readlane_b32 s100, v250, 50
	s_subb_u32 s100, s100, 0
	v_writelane_b32 v250, s100, 50
	s_nop 1
	v_readlane_b32 s100, v250, 51
	s_sub_u32 s100, s100, s101
	v_writelane_b32 v250, s100, 51
	s_nop 1
	v_readlane_b32 s100, v250, 52
	s_subb_u32 s100, s100, 0
	v_writelane_b32 v250, s100, 52
	s_nop 1
	v_readlane_b32 s100, v252, 11
	s_nop 3
	v_mov_b32_e32 v1, s100
	v_mov_b32_e32 v2, 8
	ds_write_b32 v1, v2
	s_waitcnt lgkmcnt(0)
	s_mov_b32 s100, 4

; #define LAS __attribute__((address_space(3)))
; #define STEP_BEGIN(idx, flag) if (lo <= (idx) && (idx) < hi) { for (int rep_ = 0; rep_ < (((REPEAT_MASK) & (flag)) ? 2 : 1); ++rep_) { if (prev) xcd_barrier(bar); prev = true; int lane = lane_k, wave = wave_k; size_t wz_ = 0; asm volatile("" : "+v"(lane), "+s"(wave), "+s"(wz_)); unsigned char* ws = ws_k + wz_;     const int gw = blockIdx.x * 8 + wave; (void)gw; (void)lane;
; __device__ __forceinline__ void xcd_barrier(const XcdBarrier& b) {
;     ...
;         unsigned* bar = b.bar;
;         __builtin_amdgcn_s_waitcnt(0);
;         unsigned nloc = b.st[0], nx = b.st[1];
;         if (nloc == 0u) { xcd_barrier_complete(bar, b.x, nloc, nx); b.st[0] = nloc; b.st[1] = nx; }
; __global__ void __launch_bounds__(512, 2) k_mega(MegaArgs a) {
;     ...
;             STEP_BEGIN(base + 0, F_XQ) { pg8::EpiBf16 E{XQ, 512}; run_gemm(lds, XB, (const bf16_t*)(ws + WS_W_XQ + l * SZ_XQ), MT, 512, DM, E);
;                 if (gridDim.x == 256 && blockIdx.x >= 64 && rep_ == 0) {
;                     const int xlo = l == 0 ? 12 : (l == 1 ? 20 : (l == 2 ? 29 : 37)), xhi = xlo + 2;
;                     convert_stream(a, xlo, xhi, (blockIdx.x - 64) * 8 + wave, 1536, (LAS float*)(lds + wave * 8448), lane); }
;             } STEP_END
.LBB11_624:
	s_or_b64 exec, exec, s[2:3]
	s_waitcnt lgkmcnt(0)
	s_barrier
	s_cmp_lg_u32 s100, 1
	s_cbranch_scc1 .Lsg_xq
	v_readlane_b32 s101, v249, 0
	s_and_b32 s101, s101, 6
	s_lshl_b32 s101, s101, 8
	s_addk_i32 s101, 0x400
	v_readlane_b32 s100, v250, 49
	s_sub_u32 s100, s100, s101
	v_writelane_b32 v250, s100, 49
	s_nop 1
	v_readlane_b32 s100, v250, 50
	s_subb_u32 s100, s100, 0
	v_writelane_b32 v250, s100, 50
	s_nop 1
	v_readlane_b32 s100, v250, 51
	s_sub_u32 s100, s100, s101
	v_writelane_b32 v250, s100, 51
	s_nop 1
	v_readlane_b32 s100, v250, 52
	s_subb_u32 s100, s100, 0
	v_writelane_b32 v250, s100, 52
	s_nop 1
	v_readlane_b32 s100, v252, 11
	s_nop 3
	v_mov_b32_e32 v1, s100
	v_mov_b32_e32 v2, 8
	ds_write_b32 v1, v2
	s_waitcnt lgkmcnt(0)
	s_mov_b32 s100, 4

; #define STEP_BEGIN(idx, flag) if (lo <= (idx) && (idx) < hi) { for (int rep_ = 0; rep_ < (((REPEAT_MASK) & (flag)) ? 2 : 1); ++rep_) { if (prev) xcd_barrier(bar); prev = true; int lane = lane_k, wave = wave_k; size_t wz_ = 0; asm volatile("" : "+v"(lane), "+s"(wave), "+s"(wz_)); unsigned char* ws = ws_k + wz_;     const int gw = blockIdx.x * 8 + wave; (void)gw; (void)lane;
; __device__ __forceinline__ void xcd_barrier(const XcdBarrier& b) {
;     ...
;         unsigned* bar = b.bar;
;         __builtin_amdgcn_s_waitcnt(0);
;         unsigned nloc = b.st[0], nx = b.st[1];
;         if (nloc == 0u) { xcd_barrier_complete(bar, b.x, nloc, nx); b.st[0] = nloc; b.st[1] = nx; }
; __global__ void __launch_bounds__(512, 2) k_mega(MegaArgs a) {
;     ...
;             STEP_BEGIN(base + 1, F_XATT) { fa::cross_phase(lds, XQ, KVX, XO, l); } STEP_END
.LBB11_822:
	s_or_b64 exec, exec, s[2:3]
	s_waitcnt lgkmcnt(0)
	s_barrier
	s_cmp_eq_u32 s100, 4
	s_cbranch_scc1 .Ldo_xatt
	s_branch .Lsp_xatt
.Ldo_xatt:
	v_readlane_b32 s101, v249, 0
	s_and_b32 s101, s101, 6
	s_lshl_b32 s101, s101, 8
	s_addk_i32 s101, 0x400
	v_readlane_b32 s100, v250, 49
	s_add_u32 s100, s100, s101
	v_writelane_b32 v250, s100, 49
	s_nop 1
	v_readlane_b32 s100, v250, 50
	s_addc_u32 s100, s100, 0
	v_writelane_b32 v250, s100, 50
	s_nop 1
	v_readlane_b32 s100, v250, 51
	s_add_u32 s100, s100, s101
	v_writelane_b32 v250, s100, 51
	s_nop 1
	v_readlane_b32 s100, v250, 52
	s_addc_u32 s100, s100, 0
	v_writelane_b32 v250, s100, 52
	s_nop 1
	v_readlane_b32 s100, v252, 11
	s_nop 3
	v_mov_b32_e32 v1, s100
	v_mov_b32_e32 v2, 2
	ds_write_b32 v1, v2
	s_waitcnt lgkmcnt(0)
	s_mov_b32 s100, 1

; #define STEP_BEGIN(idx, flag) if (lo <= (idx) && (idx) < hi) { for (int rep_ = 0; rep_ < (((REPEAT_MASK) & (flag)) ? 2 : 1); ++rep_) { if (prev) xcd_barrier(bar); prev = true; int lane = lane_k, wave = wave_k; size_t wz_ = 0; asm volatile("" : "+v"(lane), "+s"(wave), "+s"(wz_)); unsigned char* ws = ws_k + wz_;     const int gw = blockIdx.x * 8 + wave; (void)gw; (void)lane;
; __device__ __forceinline__ void xcd_barrier(const XcdBarrier& b) {
;     ...
;         unsigned* bar = b.bar;
;         __builtin_amdgcn_s_waitcnt(0);
;         unsigned nloc = b.st[0], nx = b.st[1];
;         if (nloc == 0u) { xcd_barrier_complete(bar, b.x, nloc, nx); b.st[0] = nloc; b.st[1] = nx; }
; __global__ void __launch_bounds__(512, 2) k_mega(MegaArgs a) {
;     ...
;                 STEP_BEGIN(base + 1, F_IDXBAND) { fa::indexer_phase(lds, QKV, SC); fa::band_phase(lds, QKV, O, a.in[11] + (size_t)i * 8 * RELSZ); } STEP_END
.LBB11_1266:
	s_or_b64 exec, exec, s[2:3]
	v_readlane_b32 s4, v249, 17
	v_readlane_b32 s18, v249, 31
	v_readlane_b32 s19, v249, 32
	s_waitcnt lgkmcnt(0)
	s_barrier
	v_readlane_b32 s5, v249, 18
	v_readlane_b32 s6, v249, 19
	v_readlane_b32 s7, v249, 20
	v_readlane_b32 s8, v249, 21
	v_readlane_b32 s9, v249, 22
	v_readlane_b32 s10, v249, 23
	v_readlane_b32 s11, v249, 24
	v_readlane_b32 s12, v249, 25
	v_readlane_b32 s13, v249, 26
	v_readlane_b32 s14, v249, 27
	v_readlane_b32 s15, v249, 28
	v_readlane_b32 s16, v249, 29
	v_readlane_b32 s17, v249, 30
	s_cmp_eq_u32 s100, 4
	s_cbranch_scc1 .Ldo_idx
	s_branch .Lsp_idx

; #define STEP_BEGIN(idx, flag) if (lo <= (idx) && (idx) < hi) { for (int rep_ = 0; rep_ < (((REPEAT_MASK) & (flag)) ? 2 : 1); ++rep_) { if (prev) xcd_barrier(bar); prev = true; int lane = lane_k, wave = wave_k; size_t wz_ = 0; asm volatile("" : "+v"(lane), "+s"(wave), "+s"(wz_)); unsigned char* ws = ws_k + wz_;     const int gw = blockIdx.x * 8 + wave; (void)gw; (void)lane;
; __device__ __forceinline__ void xcd_barrier(const XcdBarrier& b) {
;     ...
;         unsigned* bar = b.bar;
;         __builtin_amdgcn_s_waitcnt(0);
;         unsigned nloc = b.st[0], nx = b.st[1];
;         if (nloc == 0u) { xcd_barrier_complete(bar, b.x, nloc, nx); b.st[0] = nloc; b.st[1] = nx; }
; __global__ void __launch_bounds__(512, 2) k_mega(MegaArgs a) {
;     ...
;             STEP_BEGIN(base + 5, F_OUT) {
;                 unsigned* ctl = (unsigned*)(ws + WS_CTL);
;     ...
;                 pg8::EpiLnFused E{(sb == 0) ? a.in[0] : (const float*)nullptr, XB, (sb == 15) ? a.out : nullptr, DM, lng, lnb, ALPHA, ocs, st};
;                 run_gemm_fused(lds, oA, oB, MT, DM, oK, E);
;             } STEP_END
.LBB11_1879:
	s_or_b64 exec, exec, s[2:3]
	s_waitcnt lgkmcnt(0)
	s_barrier
	s_cmp_eq_u32 s100, 4
	s_cbranch_scc1 .Ldo_out
	s_cmp_lg_u32 s100, 0
	s_cbranch_scc1 .Lsp_out
	v_readlane_b32 s100, v249, 31
	v_readlane_b32 s101, v249, 32
	s_add_u32 s100, s100, 0x8000
	s_addc_u32 s101, s101, 0
	v_mbcnt_lo_u32_b32 v1, -1, 0
	v_mbcnt_hi_u32_b32 v1, -1, v1
	v_lshlrev_b32_e32 v1, 2, v1
	global_load_dword v2, v1, s[100:101] sc1
	s_waitcnt vmcnt(0)
	v_bcnt_u32_b32 v1, v2, 0
	v_cmp_lt_u32_e32 vcc, 1, v1
	s_nop 1
	s_cmp_lg_u64 vcc, 0
	s_mov_b32 s100, 2
	s_cbranch_scc1 .Lsp_out
